# prologue de-serialisation: MoBA tile-0/1 DMA issued at item start (before block selection); FFN-down epilogue gate-vector loads issued together
# speedup vs baseline: 1.0162x; 1.0064x over previous
;     __device__ __forceinline__ void operator()(const Acc& acc, const Unit& u, int wr, int wc, int fr, int fq) const {
;         const int row0 = u.pm * BM + wr * 64 + fr, col0 = u.pn * BM + wc * 32 + 4 * fq;
;         const float* g = gada + (size_t)(u.pm >> 4) * NADA;
;         f32x4 gv[2][2];
; #pragma unroll
;         for (int bj = 0; bj < 2; ++bj)
; #pragma unroll
;             for (int n = 0; n < 2; ++n) gv[bj][n] = *(const f32x4*)(g + col0 + bj * HALF + n * 16) * scale;
; #pragma unroll
;         for (int ai = 0; ai < 2; ++ai) {
;             f32x4 rr[4][2][2];
; #pragma unroll
;             for (int m = 0; m < 4; ++m)
; #pragma unroll
;                 for (int bj = 0; bj < 2; ++bj)
; #pragma unroll
;                     for (int n = 0; n < 2; ++n) rr[m][bj][n] = *(const f32x4*)(resid + (size_t)(row0 + ai * HALF + m * 16) * D_ + col0 + bj * HALF + n * 16);
; #pragma unroll
;             for (int m = 0; m < 4; ++m)
; #pragma unroll
;                 for (int bj = 0; bj < 2; ++bj)
; #pragma unroll
;                     for (int n = 0; n < 2; ++n) *(f32x4*)(out + (size_t)(row0 + ai * HALF + m * 16) * D_ + col0 + bj * HALF + n * 16) = rr[m][bj][n] + gv[bj][n] * acc[ai][bj][m][n];
.LBB0_274:
	s_ashr_i32 s18, s58, 4
	v_lshl_or_b32 v128, s59, 8, v194
	s_mul_hi_i32 s19, s18, 0x12000
	s_mul_i32 s18, s18, 0x12000
	s_add_u32 s18, s45, s18
	v_ashrrev_i32_e32 v129, 31, v128
	s_addc_u32 s19, s46, s19
	v_lshlrev_b64 v[168:169], 2, v[128:129]
	v_lshl_add_u64 v[132:133], s[18:19], 0, v[168:169]
	global_load_dwordx4 v[198:201], v[132:133], off
	global_load_dwordx4 v[202:205], v[132:133], off offset:64
	global_load_dwordx4 v[206:209], v[132:133], off offset:512
	global_load_dwordx4 v[210:213], v[132:133], off offset:576
	v_lshl_add_u64 v[186:187], s[36:37], 0, v[168:169]
	s_mov_b64 s[18:19], 0x100000
	s_and_b64 vcc, exec, s[4:5]
	v_lshl_add_u32 v128, s58, 8, v192
	v_ashrrev_i32_e32 v129, 31, v128
	v_lshlrev_b64 v[188:189], 13, v[128:129]
	v_lshl_add_u64 v[130:131], v[186:187], 0, v[188:189]
	s_waitcnt vmcnt(0)
	v_pk_mul_f32 v[170:171], v[200:201], 0.5 op_sel_hi:[1,0]
	v_pk_mul_f32 v[172:173], v[198:199], 0.5 op_sel_hi:[1,0]
	v_pk_mul_f32 v[174:175], v[204:205], 0.5 op_sel_hi:[1,0]
	v_pk_mul_f32 v[176:177], v[202:203], 0.5 op_sel_hi:[1,0]
	v_pk_mul_f32 v[178:179], v[208:209], 0.5 op_sel_hi:[1,0]
	v_pk_mul_f32 v[180:181], v[206:207], 0.5 op_sel_hi:[1,0]
	v_pk_mul_f32 v[184:185], v[210:211], 0.5 op_sel_hi:[1,0]
	v_pk_mul_f32 v[182:183], v[212:213], 0.5 op_sel_hi:[1,0]
	global_load_dwordx4 v[198:201], v[130:131], off
	global_load_dwordx4 v[202:205], v[130:131], off offset:64
	global_load_dwordx4 v[206:209], v[130:131], off offset:512
	global_load_dwordx4 v[210:213], v[130:131], off offset:576
	v_or_b32_e32 v130, 16, v128
	v_ashrrev_i32_e32 v131, 31, v130
	v_lshlrev_b64 v[234:235], 13, v[130:131]
	v_lshl_add_u64 v[130:131], v[186:187], 0, v[234:235]
	global_load_dwordx4 v[214:217], v[130:131], off
	global_load_dwordx4 v[218:221], v[130:131], off offset:64
	global_load_dwordx4 v[222:225], v[130:131], off offset:512
	global_load_dwordx4 v[226:229], v[130:131], off offset:576
	v_or_b32_e32 v130, 32, v128
	v_ashrrev_i32_e32 v131, 31, v130
	v_lshlrev_b64 v[236:237], 13, v[130:131]
	v_or_b32_e32 v128, 48, v128
	v_lshl_add_u64 v[130:131], v[186:187], 0, v[236:237]
	v_ashrrev_i32_e32 v129, 31, v128
	global_load_dwordx4 v[230:233], v[130:131], off
	global_load_dwordx4 v[152:155], v[130:131], off offset:64
	global_load_dwordx4 v[148:151], v[130:131], off offset:512
	global_load_dwordx4 v[140:143], v[130:131], off offset:576
	v_lshlrev_b64 v[190:191], 13, v[128:129]
	v_lshl_add_u64 v[128:129], v[186:187], 0, v[190:191]
	global_load_dwordx4 v[144:147], v[128:129], off
	global_load_dwordx4 v[136:139], v[128:129], off offset:64
	global_load_dwordx4 v[132:135], v[128:129], off offset:512
	s_nop 0
	global_load_dwordx4 v[128:131], v[128:129], off offset:576
	s_waitcnt vmcnt(15)
	v_pk_fma_f32 v[124:125], v[124:125], v[172:173], v[198:199]
	v_lshl_add_u64 v[198:199], s[24:25], 0, v[188:189]
	v_lshl_add_u64 v[198:199], v[198:199], 0, v[168:169]
	s_waitcnt vmcnt(13)
	v_pk_fma_f32 v[114:115], v[114:115], v[178:179], v[208:209]
	v_pk_fma_f32 v[112:113], v[112:113], v[180:181], v[206:207]
	global_store_dwordx4 v[198:199], v[112:115], off offset:512
	s_waitcnt vmcnt(13)
	v_pk_fma_f32 v[110:111], v[110:111], v[182:183], v[212:213]
	s_waitcnt vmcnt(10)
	v_pk_fma_f32 v[98:99], v[98:99], v[178:179], v[224:225]
	v_lshl_add_u64 v[112:113], s[24:25], 0, v[234:235]
	v_lshl_add_u64 v[112:113], v[112:113], 0, v[168:169]
	v_pk_fma_f32 v[96:97], v[96:97], v[180:181], v[222:223]
	global_store_dwordx4 v[112:113], v[96:99], off offset:512
	v_pk_fma_f32 v[108:109], v[108:109], v[184:185], v[210:211]
	s_waitcnt vmcnt(10)
	v_pk_fma_f32 v[94:95], v[94:95], v[182:183], v[228:229]
	v_lshl_add_u64 v[96:97], s[24:25], 0, v[236:237]
	v_lshl_add_u64 v[96:97], v[96:97], 0, v[168:169]
	s_waitcnt vmcnt(7)
	v_pk_fma_f32 v[82:83], v[82:83], v[178:179], v[150:151]
	v_pk_fma_f32 v[80:81], v[80:81], v[180:181], v[148:149]
	global_store_dwordx4 v[96:97], v[80:83], off offset:512
	s_waitcnt vmcnt(7)
	v_pk_fma_f32 v[74:75], v[74:75], v[182:183], v[142:143]
	v_pk_fma_f32 v[72:73], v[72:73], v[184:185], v[140:141]
	v_lshl_add_u64 v[80:81], s[24:25], 0, v[190:191]
	v_pk_fma_f32 v[92:93], v[92:93], v[184:185], v[226:227]
	global_store_dwordx4 v[96:97], v[72:75], off offset:576
	v_lshl_add_u64 v[80:81], v[80:81], 0, v[168:169]
	v_pk_fma_f32 v[126:127], v[126:127], v[170:171], v[200:201]
	s_waitcnt vmcnt(7)
	v_pk_fma_f32 v[74:75], v[86:87], v[170:171], v[146:147]
	v_pk_fma_f32 v[72:73], v[84:85], v[172:173], v[144:145]
	v_pk_fma_f32 v[122:123], v[122:123], v[174:175], v[204:205]
	v_pk_fma_f32 v[120:121], v[120:121], v[176:177], v[202:203]
	global_store_dwordx4 v[198:199], v[108:111], off offset:576
	v_pk_fma_f32 v[106:107], v[106:107], v[174:175], v[220:221]
	v_pk_fma_f32 v[104:105], v[104:105], v[176:177], v[218:219]
	v_pk_fma_f32 v[110:111], v[118:119], v[170:171], v[216:217]
	v_pk_fma_f32 v[108:109], v[116:117], v[172:173], v[214:215]
	global_store_dwordx4 v[112:113], v[92:95], off offset:576
	v_pk_fma_f32 v[90:91], v[90:91], v[174:175], v[154:155]
	v_pk_fma_f32 v[88:89], v[88:89], v[176:177], v[152:153]
	v_pk_fma_f32 v[94:95], v[102:103], v[170:171], v[232:233]
	v_pk_fma_f32 v[92:93], v[100:101], v[172:173], v[230:231]
	global_store_dwordx4 v[80:81], v[72:75], off
	s_waitcnt vmcnt(8)
	v_pk_fma_f32 v[70:71], v[70:71], v[178:179], v[134:135]
	v_pk_fma_f32 v[68:69], v[68:69], v[180:181], v[132:133]
	v_pk_fma_f32 v[74:75], v[78:79], v[174:175], v[138:139]
	v_pk_fma_f32 v[72:73], v[76:77], v[176:177], v[136:137]
	s_waitcnt vmcnt(7)
;     __device__ __forceinline__ void operator()(const Acc& acc, const Unit& u, int wr, int wc, int fr, int fq) const {
;     ...
;         for (int ai = 0; ai < 2; ++ai) {
;             f32x4 rr[4][2][2];
; #pragma unroll
;             for (int m = 0; m < 4; ++m)
; #pragma unroll
;                 for (int bj = 0; bj < 2; ++bj)
; #pragma unroll
;                     for (int n = 0; n < 2; ++n) rr[m][bj][n] = *(const f32x4*)(resid + (size_t)(row0 + ai * HALF + m * 16) * D_ + col0 + bj * HALF + n * 16);
; #pragma unroll
;             for (int m = 0; m < 4; ++m)
; #pragma unroll
;                 for (int bj = 0; bj < 2; ++bj)
; #pragma unroll
;                     for (int n = 0; n < 2; ++n) *(f32x4*)(out + (size_t)(row0 + ai * HALF + m * 16) * D_ + col0 + bj * HALF + n * 16) = rr[m][bj][n] + gv[bj][n] * acc[ai][bj][m][n];
	v_pk_fma_f32 v[66:67], v[66:67], v[182:183], v[130:131]
	v_pk_fma_f32 v[64:65], v[64:65], v[184:185], v[128:129]
	v_lshl_add_u64 v[130:131], v[188:189], 0, s[18:19]
	global_store_dwordx4 v[198:199], v[124:127], off
	global_store_dwordx4 v[198:199], v[120:123], off offset:64
	global_store_dwordx4 v[112:113], v[108:111], off
	global_store_dwordx4 v[112:113], v[104:107], off offset:64
	global_store_dwordx4 v[96:97], v[92:95], off
	global_store_dwordx4 v[96:97], v[88:91], off offset:64
	global_store_dwordx4 v[80:81], v[72:75], off offset:64
	global_store_dwordx4 v[80:81], v[68:71], off offset:512
	global_store_dwordx4 v[80:81], v[64:67], off offset:576
	s_mov_b64 s[18:19], 0x120000
	v_lshl_add_u64 v[132:133], v[188:189], 0, s[18:19]
	v_lshl_add_u64 v[64:65], v[186:187], 0, v[130:131]
	global_load_dwordx4 v[94:97], v[64:65], off
	global_load_dwordx4 v[98:101], v[64:65], off offset:64
	global_load_dwordx4 v[102:105], v[64:65], off offset:512
	global_load_dwordx4 v[106:109], v[64:65], off offset:576
	v_lshl_add_u64 v[64:65], v[186:187], 0, v[132:133]
	s_mov_b64 s[18:19], 0x140000
	global_load_dwordx4 v[110:113], v[64:65], off
	global_load_dwordx4 v[114:117], v[64:65], off offset:64
	global_load_dwordx4 v[118:121], v[64:65], off offset:512
	global_load_dwordx4 v[122:125], v[64:65], off offset:576
	v_lshl_add_u64 v[134:135], v[188:189], 0, s[18:19]
	v_lshl_add_u64 v[64:65], v[186:187], 0, v[134:135]
	s_mov_b64 s[18:19], 0x160000
	global_load_dwordx4 v[126:129], v[64:65], off
	global_load_dwordx4 v[88:91], v[64:65], off offset:64
	global_load_dwordx4 v[84:87], v[64:65], off offset:512
	global_load_dwordx4 v[80:83], v[64:65], off offset:576
	v_lshl_add_u64 v[92:93], v[188:189], 0, s[18:19]
	v_lshl_add_u64 v[64:65], v[186:187], 0, v[92:93]
	global_load_dwordx4 v[76:79], v[64:65], off
	global_load_dwordx4 v[72:75], v[64:65], off offset:64
	global_load_dwordx4 v[68:71], v[64:65], off offset:512
	s_nop 0
	global_load_dwordx4 v[64:67], v[64:65], off offset:576
	s_mov_b64 s[18:19], -1
	s_waitcnt vmcnt(15)
	v_pk_fma_f32 v[60:61], v[60:61], v[172:173], v[94:95]
	v_lshl_add_u64 v[94:95], s[24:25], 0, v[130:131]
	v_lshl_add_u64 v[94:95], v[94:95], 0, v[168:169]
	s_waitcnt vmcnt(13)
	v_pk_fma_f32 v[50:51], v[50:51], v[178:179], v[104:105]
	v_pk_fma_f32 v[48:49], v[48:49], v[180:181], v[102:103]
	global_store_dwordx4 v[94:95], v[48:51], off offset:512
	s_waitcnt vmcnt(10)
	v_pk_fma_f32 v[34:35], v[34:35], v[178:179], v[120:121]
	v_pk_fma_f32 v[32:33], v[32:33], v[180:181], v[118:119]
	v_lshl_add_u64 v[48:49], s[24:25], 0, v[132:133]
	v_lshl_add_u64 v[48:49], v[48:49], 0, v[168:169]
	global_store_dwordx4 v[48:49], v[32:35], off offset:512
	s_waitcnt vmcnt(7)
	v_pk_fma_f32 v[18:19], v[18:19], v[178:179], v[86:87]
	v_pk_fma_f32 v[16:17], v[16:17], v[180:181], v[84:85]
	v_lshl_add_u64 v[32:33], s[24:25], 0, v[134:135]
	v_lshl_add_u64 v[32:33], v[32:33], 0, v[168:169]
	global_store_dwordx4 v[32:33], v[16:19], off offset:512
	s_waitcnt vmcnt(7)
	v_pk_fma_f32 v[10:11], v[10:11], v[182:183], v[82:83]
	v_pk_fma_f32 v[8:9], v[8:9], v[184:185], v[80:81]
	v_lshl_add_u64 v[16:17], s[24:25], 0, v[92:93]
	v_pk_fma_f32 v[46:47], v[46:47], v[182:183], v[108:109]
	v_pk_fma_f32 v[44:45], v[44:45], v[184:185], v[106:107]
	v_pk_fma_f32 v[30:31], v[30:31], v[182:183], v[124:125]
	v_pk_fma_f32 v[28:29], v[28:29], v[184:185], v[122:123]
	global_store_dwordx4 v[32:33], v[8:11], off offset:576
	v_lshl_add_u64 v[16:17], v[16:17], 0, v[168:169]
	v_pk_fma_f32 v[62:63], v[62:63], v[170:171], v[96:97]
	s_waitcnt vmcnt(7)
	v_pk_fma_f32 v[10:11], v[22:23], v[170:171], v[78:79]
	v_pk_fma_f32 v[8:9], v[20:21], v[172:173], v[76:77]
	v_pk_fma_f32 v[58:59], v[58:59], v[174:175], v[100:101]
	v_pk_fma_f32 v[56:57], v[56:57], v[176:177], v[98:99]
	global_store_dwordx4 v[94:95], v[44:47], off offset:576
	v_pk_fma_f32 v[42:43], v[42:43], v[174:175], v[116:117]
	v_pk_fma_f32 v[40:41], v[40:41], v[176:177], v[114:115]
	v_pk_fma_f32 v[46:47], v[54:55], v[170:171], v[112:113]
	v_pk_fma_f32 v[44:45], v[52:53], v[172:173], v[110:111]
	global_store_dwordx4 v[48:49], v[28:31], off offset:576
	v_pk_fma_f32 v[26:27], v[26:27], v[174:175], v[90:91]
	v_pk_fma_f32 v[24:25], v[24:25], v[176:177], v[88:89]
	v_pk_fma_f32 v[30:31], v[38:39], v[170:171], v[128:129]
	v_pk_fma_f32 v[28:29], v[36:37], v[172:173], v[126:127]
	global_store_dwordx4 v[16:17], v[8:11], off
	s_waitcnt vmcnt(8)
	v_pk_fma_f32 v[6:7], v[6:7], v[178:179], v[70:71]
	v_pk_fma_f32 v[4:5], v[4:5], v[180:181], v[68:69]
	v_pk_fma_f32 v[10:11], v[14:15], v[174:175], v[74:75]
	v_pk_fma_f32 v[8:9], v[12:13], v[176:177], v[72:73]
	s_waitcnt vmcnt(7)
	v_pk_fma_f32 v[2:3], v[2:3], v[182:183], v[66:67]
	v_pk_fma_f32 v[0:1], v[0:1], v[184:185], v[64:65]
	global_store_dwordx4 v[94:95], v[60:63], off
	global_store_dwordx4 v[94:95], v[56:59], off offset:64
	global_store_dwordx4 v[48:49], v[44:47], off
	global_store_dwordx4 v[48:49], v[40:43], off offset:64
	global_store_dwordx4 v[32:33], v[28:31], off
	global_store_dwordx4 v[32:33], v[24:27], off offset:64
	global_store_dwordx4 v[16:17], v[8:11], off offset:64
	global_store_dwordx4 v[16:17], v[4:7], off offset:512
	global_store_dwordx4 v[16:17], v[0:3], off offset:576
	s_cbranch_vccnz .LBB0_259
	s_andn2_b64 vcc, exec, s[8:9]
	s_cbranch_vccnz .LBB0_258
	s_barrier
	s_branch .LBB0_258

; #define LAS __attribute__((address_space(3)))
; __device__ __forceinline__ unsigned pkbf(float a, float b) { return cvt_pk_bf16(a, b); }
; #define MFMA32(a, b, c) __builtin_amdgcn_mfma_f32_32x32x16_bf16((a), (b), (c), 0, 0, 0)
; __device__ __forceinline__ void phase_moba_mfma(const Params& p, LAS unsigned char* lds, unsigned lds_base) {
;     ...
;         const int qb = 15 - (it >> 6), bh = it & 63, b = bh >> 4, h = bh & 15;
;         const size_t rowb = (size_t)b * T_;
;         __syncthreads();
;         { const int r = tid >> 5, c4 = (tid & 31) * 4; const f32x4 kv = *(const f32x4*)(KM + ((size_t)(bh * 16 + r)) * 128 + c4);
;           u32x2 w = {pkbf(kv[0], kv[1]), pkbf(kv[2], kv[3])}; *(LAS u32x2*)(lds + OFF_KM + r * KST + c4 * 2) = w; *(LAS u32x2*)(lds + OFF_KM + (r + 16) * KST + c4 * 2) = (u32x2){0u, 0u}; }
;         { LAS float* bts = (LAS float*)(lds + OFF_BT); bts[tid] = BT[h * 4096 + tid]; bts[tid + 512] = BT[h * 4096 + tid + 512]; }
;         const float c31 = BT[h * 4096 + 1023];
;         const int q0 = qb * 256 + 32 * wave;
;         bf16_t* qptr = MBQ + (rowb + q0 + i32) * D_ + h * 128;
;         bf16x8 qf[8];
; #pragma unroll
;         for (int kc = 0; kc < 8; ++kc) qf[kc] = *(const bf16x8*)(qptr + 16 * kc + 8 * hh);
;         __syncthreads();
;         unsigned sel = 0;
;         {
;             f32x16 g;
; #pragma unroll
;             for (int r = 0; r < 16; ++r) g[r] = 0.f;
; #pragma unroll
;             for (int kc = 0; kc < 8; ++kc) { const bf16x8 a = *(const LAS bf16x8*)(lds + OFF_KM + i32 * KST + (16 * kc + 8 * hh) * 2); g = MFMA32(a, qf[kc], g); }
.LBB0_735:
	s_and_b32 s0, s2, 63
	v_lshl_add_u32 v2, s0, 4, v181
	s_and_b32 s11, s2, 15
	v_ashrrev_i32_e32 v3, 31, v2
	s_ashr_i32 s4, s2, 6
	v_lshlrev_b64 v[2:3], 9, v[2:3]
	v_lshl_add_u32 v4, s11, 12, v179
	s_sub_i32 s36, 15, s4
	v_lshl_add_u64 v[2:3], v[188:189], 0, v[2:3]
	v_ashrrev_i32_e32 v5, 31, v4
	s_barrier
	v_lshl_add_u64 v[6:7], v[4:5], 2, s[8:9]
	global_load_dwordx4 v[2:5], v[2:3], off
	s_nop 0
	global_load_dword v1, v[6:7], off
	global_load_dword v8, v[6:7], off offset:2048
	s_lshl_b32 s10, s36, 8
	s_lshl_b32 s1, s2, 8
	s_add_i32 s6, s10, s18
	s_and_b32 s7, s1, 0x3000
	s_lshl_b32 s0, s11, 14
	s_ashr_i32 s1, s6, 31
	s_add_u32 s5, s6, s7
	s_addc_u32 s1, s1, 0
	v_mov_b32_e32 v7, s1
	v_or_b32_e32 v6, s5, v178
	v_readlane_b32 s12, v254, 57
	v_lshlrev_b64 v[6:7], 12, v[6:7]
	v_readlane_b32 s13, v254, 58
	s_lshl_b32 s68, s11, 8
	v_mov_b32_e32 v9, s0
	v_lshl_add_u64 v[6:7], s[12:13], 0, v[6:7]
	v_lshl_add_u64 v[202:203], v[6:7], 0, s[68:69]
	v_lshl_add_u64 v[6:7], v[202:203], 0, v[198:199]
	global_load_dwordx4 v[130:133], v[6:7], off
	global_load_dwordx4 v[134:137], v[6:7], off offset:32
	global_load_dwordx4 v[138:141], v[6:7], off offset:64
	global_load_dwordx4 v[142:145], v[6:7], off offset:96
	global_load_dwordx4 v[146:149], v[6:7], off offset:128
	global_load_dwordx4 v[150:153], v[6:7], off offset:160
	global_load_dwordx4 v[154:157], v[6:7], off offset:192
	ds_write_b64 v215, v[196:197] offset:4352
	global_load_dwordx4 v[158:161], v[6:7], off offset:224
	global_load_dword v204, v9, s[8:9] offset:4092
	v_mov_b32_e32 v174, s68
	s_add_i32 s48, s7, s10
	s_mov_b32 s0, s48
	s_lshl_b32 s0, s0, 12
	v_readfirstlane_b32 s1, v174
	s_nop 0
	s_add_i32 s0, s0, s1
	s_add_u32 s40, s22, s0
	s_addc_u32 s41, s23, 0
	s_add_u32 s42, s34, s0
	s_addc_u32 s43, s35, 0
	s_mov_b32 s44, 0
	s_mov_b32 s47, 0xc000
	s_lshl_b32 s45, s18, 6
	s_add_i32 s44, s44, s45
	s_add_i32 s44, s44, 16
	s_add_i32 s47, s47, s45
	s_add_i32 s47, s47, 16
	s_mov_b32 m0, s44
	s_nop 0
	global_load_lds_dwordx4 v224, s[40:41]
	s_add_i32 m0, s44, 0x400
	s_nop 0
	global_load_lds_dwordx4 v225, s[40:41]
	s_mov_b32 m0, s47
	s_nop 0
	global_load_lds_dwordx4 v226, s[42:43]
	s_add_i32 m0, s47, 0x400
	s_nop 0
	global_load_lds_dwordx4 v227, s[42:43]
	s_add_i32 s48, s48, 64
	s_mov_b32 s0, s48
	s_lshl_b32 s0, s0, 12
	v_readfirstlane_b32 s1, v174
	s_nop 0
	s_add_i32 s0, s0, s1
	s_add_u32 s40, s22, s0
	s_addc_u32 s41, s23, 0
	s_add_u32 s42, s34, s0
	s_addc_u32 s43, s35, 0
	s_mov_b32 s44, 0x4000
	s_mov_b32 s47, 0x16000
	s_lshl_b32 s45, s18, 6
	s_add_i32 s44, s44, s45
	s_add_i32 s44, s44, 16
	s_add_i32 s47, s47, s45
	s_add_i32 s47, s47, 16
	s_mov_b32 m0, s44
	s_nop 0
	global_load_lds_dwordx4 v224, s[40:41]
	s_add_i32 m0, s44, 0x400
	s_nop 0
	global_load_lds_dwordx4 v225, s[40:41]
	s_mov_b32 m0, s47
	s_nop 0
	global_load_lds_dwordx4 v226, s[42:43]
	s_add_i32 m0, s47, 0x400
	s_nop 0
	global_load_lds_dwordx4 v227, s[42:43]
	s_cmp_gt_i32 s4, 14
	s_cselect_b64 s[0:1], -1, 0
	s_waitcnt vmcnt(19)
	v_cvt_pk_bf16_f32 v2, v2, v3
	v_cvt_pk_bf16_f32 v3, v4, v5
	ds_write_b64 v215, v[2:3]
	s_waitcnt vmcnt(17)
	ds_write2st64_b32 v191, v1, v8 offset1:8
	s_waitcnt lgkmcnt(0)
	s_barrier
	ds_read_b128 v[2:5], v216
	ds_read_b128 v[18:21], v216 offset:32
	s_waitcnt vmcnt(16) lgkmcnt(1)
	v_mfma_f32_32x32x16_bf16 v[2:17], v[2:5], v[130:133], 0
	s_waitcnt vmcnt(15) lgkmcnt(0)
	v_mfma_f32_32x32x16_bf16 v[2:17], v[18:21], v[134:137], v[2:17]
	ds_read_b128 v[18:21], v216 offset:64
	ds_read_b128 v[22:25], v216 offset:96
	s_waitcnt vmcnt(14) lgkmcnt(1)
	v_mfma_f32_32x32x16_bf16 v[2:17], v[18:21], v[138:141], v[2:17]
	s_waitcnt vmcnt(13) lgkmcnt(0)
	v_mfma_f32_32x32x16_bf16 v[2:17], v[22:25], v[142:145], v[2:17]
	ds_read_b128 v[18:21], v216 offset:128
	ds_read_b128 v[22:25], v216 offset:160
	s_waitcnt vmcnt(12) lgkmcnt(1)
	v_mfma_f32_32x32x16_bf16 v[2:17], v[18:21], v[146:149], v[2:17]
	s_waitcnt vmcnt(11) lgkmcnt(0)
	v_mfma_f32_32x32x16_bf16 v[2:17], v[22:25], v[150:153], v[2:17]
	ds_read_b128 v[18:21], v216 offset:192
	ds_read_b128 v[22:25], v216 offset:224
	s_waitcnt vmcnt(10) lgkmcnt(1)
	v_mfma_f32_32x32x16_bf16 v[2:17], v[18:21], v[154:157], v[2:17]
	s_waitcnt vmcnt(9) lgkmcnt(0)
	v_mfma_f32_32x32x16_bf16 v[2:17], v[22:25], v[158:161], v[2:17]
	s_nop 11
	ds_bpermute_b32 v1, v193, v2
	ds_bpermute_b32 v10, v193, v3
	ds_bpermute_b32 v14, v193, v7
	ds_bpermute_b32 v11, v193, v4
	ds_bpermute_b32 v12, v193, v5
	s_waitcnt lgkmcnt(4)
	v_cndmask_b32_e64 v17, v1, v2, s[38:39]
	ds_bpermute_b32 v13, v193, v6
	v_cmp_nlg_f32_e32 vcc, s29, v17
	s_or_b64 vcc, s[0:1], vcc
	s_waitcnt lgkmcnt(4)
	v_cndmask_b32_e64 v18, v10, v3, s[38:39]
	v_cndmask_b32_e64 v1, v2, v1, s[38:39]
	v_cndmask_b32_e64 v2, v3, v10, s[38:39]
	s_waitcnt lgkmcnt(3)
	v_cndmask_b32_e64 v10, v14, v7, s[38:39]
	v_cndmask_b32_e64 v7, v7, v14, s[38:39]
	v_cndmask_b32_e32 v14, v17, v217, vcc
	s_cmp_lt_i32 s4, 14
	s_cselect_b64 s[74:75], -1, 0
	v_cmp_gt_f32_e64 s[0:1], v18, v14
	s_and_b64 s[0:1], s[74:75], s[0:1]
	s_waitcnt lgkmcnt(2)
	v_cndmask_b32_e64 v19, v11, v4, s[38:39]
	s_waitcnt lgkmcnt(1)
	v_cndmask_b32_e64 v20, v12, v5, s[38:39]
	v_cndmask_b32_e64 v3, v4, v11, s[38:39]
	v_cndmask_b32_e64 v4, v5, v12, s[38:39]
	s_waitcnt lgkmcnt(0)
; __device__ __forceinline__ void phase_moba_mfma(const Params& p, LAS unsigned char* lds, unsigned lds_base) {
;     ...
;             float gate[16];
; #pragma unroll
;             for (int j = 0; j < 16; ++j) { const int half = (j >> 2) & 1, r = (j & 3) + 4 * (j >> 3); const float og = __shfl_xor(g[r], 32); gate[j] = (hh == half) ? g[r] : og; }
; #pragma unroll
;             for (int rep = 0; rep < 3; ++rep) { float best = NINF; int bi = -1;
; #pragma unroll
;                 for (int j = 0; j < 16; ++j) if (j < qb && !((sel >> j) & 1u) && gate[j] > best) { best = gate[j]; bi = j; }
;                 if (bi >= 0) sel |= 1u << bi; }
	v_cndmask_b32_e64 v5, v13, v6, s[38:39]
	v_cndmask_b32_e64 v6, v6, v13, s[38:39]
	v_cndmask_b32_e64 v13, 0, -1, vcc
	v_cndmask_b32_e64 v14, v14, v18, s[0:1]
	s_cmp_lt_i32 s4, 13
	v_cndmask_b32_e64 v13, v13, 1, s[0:1]
	s_cselect_b64 s[72:73], -1, 0
	v_cmp_gt_f32_e64 s[0:1], v19, v14
	s_and_b64 s[0:1], s[72:73], s[0:1]
	s_cmp_lt_i32 s4, 12
	v_cndmask_b32_e64 v14, v14, v19, s[0:1]
	v_cndmask_b32_e64 v13, v13, 2, s[0:1]
	s_cselect_b64 s[70:71], -1, 0
	v_cmp_gt_f32_e64 s[0:1], v20, v14
	s_and_b64 s[0:1], s[70:71], s[0:1]
	s_cmp_lt_i32 s4, 11
	v_cndmask_b32_e64 v14, v14, v20, s[0:1]
	v_cndmask_b32_e64 v13, v13, 3, s[0:1]
	s_cselect_b64 s[66:67], -1, 0
	v_cmp_gt_f32_e64 s[0:1], v1, v14
	s_and_b64 s[0:1], s[66:67], s[0:1]
	s_cmp_lt_i32 s4, 10
	v_cndmask_b32_e64 v14, v14, v1, s[0:1]
	v_cndmask_b32_e64 v13, v13, 4, s[0:1]
	s_cselect_b64 s[64:65], -1, 0
	v_cmp_gt_f32_e64 s[0:1], v2, v14
	s_and_b64 s[0:1], s[64:65], s[0:1]
	s_cmp_lt_i32 s4, 9
	v_cndmask_b32_e64 v14, v14, v2, s[0:1]
	v_cndmask_b32_e64 v13, v13, 5, s[0:1]
	s_cselect_b64 s[62:63], -1, 0
	v_cmp_gt_f32_e64 s[0:1], v3, v14
	s_and_b64 s[0:1], s[62:63], s[0:1]
	s_cmp_lt_i32 s4, 8
	v_cndmask_b32_e64 v14, v14, v3, s[0:1]
	v_cndmask_b32_e64 v13, v13, 6, s[0:1]
	s_cselect_b64 s[60:61], -1, 0
	v_cmp_gt_f32_e64 s[0:1], v4, v14
	s_and_b64 s[0:1], s[60:61], s[0:1]
	s_cmp_lt_i32 s4, 7
	v_cndmask_b32_e64 v14, v14, v4, s[0:1]
	ds_bpermute_b32 v15, v193, v8
	v_cndmask_b32_e64 v13, v13, 7, s[0:1]
	s_cselect_b64 s[58:59], -1, 0
	v_cmp_gt_f32_e64 s[0:1], v5, v14
	s_and_b64 s[0:1], s[58:59], s[0:1]
	s_cmp_lt_i32 s4, 6
	v_cndmask_b32_e64 v14, v14, v5, s[0:1]
	ds_bpermute_b32 v16, v193, v9
	v_cndmask_b32_e64 v13, v13, 8, s[0:1]
	s_cselect_b64 s[56:57], -1, 0
	v_cmp_gt_f32_e64 s[0:1], v10, v14
	s_and_b64 s[0:1], s[56:57], s[0:1]
	s_waitcnt lgkmcnt(1)
	v_cndmask_b32_e64 v11, v15, v8, s[38:39]
	v_cndmask_b32_e64 v14, v14, v10, s[0:1]
	s_cmp_lt_i32 s4, 5
	v_cndmask_b32_e64 v13, v13, 9, s[0:1]
	s_cselect_b64 s[54:55], -1, 0
	v_cmp_gt_f32_e64 s[0:1], v11, v14
	s_and_b64 s[0:1], s[54:55], s[0:1]
	s_waitcnt lgkmcnt(0)
	v_cndmask_b32_e64 v12, v16, v9, s[38:39]
	v_cndmask_b32_e64 v14, v14, v11, s[0:1]
	s_cmp_lt_i32 s4, 4
	v_cndmask_b32_e64 v13, v13, 10, s[0:1]
	s_cselect_b64 s[52:53], -1, 0
	v_cmp_gt_f32_e64 s[0:1], v12, v14
	s_and_b64 s[0:1], s[52:53], s[0:1]
	s_cmp_lt_i32 s4, 3
	v_cndmask_b32_e64 v14, v14, v12, s[0:1]
	v_cndmask_b32_e64 v13, v13, 11, s[0:1]
	s_cselect_b64 s[16:17], -1, 0
	v_cmp_gt_f32_e64 s[0:1], v6, v14
	s_and_b64 s[0:1], s[16:17], s[0:1]
	s_cmp_lt_i32 s4, 2
	v_cndmask_b32_e64 v14, v14, v6, s[0:1]
	v_cndmask_b32_e64 v13, v13, 12, s[0:1]
	s_cselect_b64 s[14:15], -1, 0
	v_cmp_gt_f32_e64 s[0:1], v7, v14
	s_and_b64 s[0:1], s[14:15], s[0:1]
	v_cndmask_b32_e64 v8, v8, v15, s[38:39]
	v_cndmask_b32_e64 v14, v14, v7, s[0:1]
	s_cmp_lt_i32 s4, 1
	v_cndmask_b32_e64 v13, v13, 13, s[0:1]
	s_cselect_b64 s[12:13], -1, 0
	v_cmp_gt_f32_e64 s[0:1], v8, v14
	s_and_b64 s[0:1], s[12:13], s[0:1]
	v_cndmask_b32_e64 v9, v9, v16, s[38:39]
	v_cndmask_b32_e64 v14, v14, v8, s[0:1]
	s_cmp_lt_i32 s4, 0
	v_cndmask_b32_e64 v13, v13, 14, s[0:1]
	s_cselect_b64 s[4:5], -1, 0
	v_cmp_gt_f32_e64 s[0:1], v9, v14
	s_and_b64 s[0:1], s[4:5], s[0:1]
	s_nop 0
	v_cndmask_b32_e64 v13, v13, 15, s[0:1]
	v_lshlrev_b32_e64 v14, v13, 1
	v_cmp_lt_i32_e64 s[0:1], -1, v13
	s_nop 1
	v_cndmask_b32_e64 v13, 0, v14, s[0:1]
	v_and_b32_e32 v14, 1, v13
	v_cmp_eq_u32_e64 s[0:1], 1, v14
	v_and_b32_e32 v15, 2, v13
	s_or_b64 s[0:1], vcc, s[0:1]
	v_cmp_eq_u32_e64 s[40:41], 0, v15
	v_cndmask_b32_e64 v15, v17, v217, s[0:1]
	v_cndmask_b32_e64 v14, 0, -1, s[0:1]
	s_and_b64 s[40:41], s[74:75], s[40:41]
	v_cmp_gt_f32_e64 s[0:1], v18, v15
	v_and_b32_e32 v16, 4, v13
	s_and_b64 s[0:1], s[40:41], s[0:1]
	v_cmp_eq_u32_e64 s[42:43], 0, v16
	v_cndmask_b32_e64 v15, v15, v18, s[0:1]
	s_and_b64 s[42:43], s[72:73], s[42:43]
	v_cndmask_b32_e64 v14, v14, 1, s[0:1]
	v_cmp_gt_f32_e64 s[0:1], v19, v15
	v_and_b32_e32 v21, 8, v13
	s_and_b64 s[0:1], s[42:43], s[0:1]
	v_cmp_eq_u32_e64 s[44:45], 0, v21
	v_cndmask_b32_e64 v15, v15, v19, s[0:1]
	s_and_b64 s[44:45], s[70:71], s[44:45]
	v_cndmask_b32_e64 v14, v14, 2, s[0:1]
	v_cmp_gt_f32_e64 s[0:1], v20, v15
	v_and_b32_e32 v22, 16, v13
	s_and_b64 s[0:1], s[44:45], s[0:1]
	v_cmp_eq_u32_e64 s[46:47], 0, v22
	v_cndmask_b32_e64 v15, v15, v20, s[0:1]
	s_and_b64 s[46:47], s[66:67], s[46:47]
	v_cndmask_b32_e64 v14, v14, 3, s[0:1]
	v_cmp_gt_f32_e64 s[0:1], v1, v15
	v_and_b32_e32 v23, 32, v13
	s_and_b64 s[0:1], s[46:47], s[0:1]
	v_cmp_eq_u32_e64 s[48:49], 0, v23
	v_cndmask_b32_e64 v15, v15, v1, s[0:1]
	s_and_b64 s[48:49], s[64:65], s[48:49]
	v_cndmask_b32_e64 v14, v14, 4, s[0:1]
	v_cmp_gt_f32_e64 s[0:1], v2, v15
	v_and_b32_e32 v24, 64, v13
	s_and_b64 s[0:1], s[48:49], s[0:1]
	v_cmp_eq_u32_e64 s[50:51], 0, v24
	v_cndmask_b32_e64 v15, v15, v2, s[0:1]
	s_and_b64 s[50:51], s[62:63], s[50:51]
	v_cndmask_b32_e64 v14, v14, 5, s[0:1]
	v_cmp_gt_f32_e64 s[0:1], v3, v15
	v_and_b32_e32 v25, 0x80, v13
	s_and_b64 s[0:1], s[50:51], s[0:1]
	v_cndmask_b32_e64 v14, v14, 6, s[0:1]
	v_cndmask_b32_e64 v15, v15, v3, s[0:1]
	v_cmp_eq_u32_e64 s[0:1], 0, v25
	s_and_b64 s[40:41], s[60:61], s[0:1]
	v_cmp_gt_f32_e64 s[0:1], v4, v15
	s_and_b64 s[0:1], s[40:41], s[0:1]
	v_and_b32_e32 v16, 0x100, v13
	v_cndmask_b32_e64 v14, v14, 7, s[0:1]
	v_cndmask_b32_e64 v15, v15, v4, s[0:1]
	v_cmp_eq_u32_e64 s[0:1], 0, v16
	s_and_b64 s[40:41], s[58:59], s[0:1]
	v_cmp_gt_f32_e64 s[0:1], v5, v15
	s_and_b64 s[0:1], s[40:41], s[0:1]
	v_and_b32_e32 v16, 0x200, v13
	v_cndmask_b32_e64 v14, v14, 8, s[0:1]
	v_cndmask_b32_e64 v15, v15, v5, s[0:1]
	v_cmp_eq_u32_e64 s[0:1], 0, v16
	s_and_b64 s[40:41], s[56:57], s[0:1]
; #define LAS __attribute__((address_space(3)))
; __device__ __forceinline__ void phase_moba_mfma(const Params& p, LAS unsigned char* lds, unsigned lds_base) {
;     ...
;             for (int rep = 0; rep < 3; ++rep) { float best = NINF; int bi = -1;
; #pragma unroll
;                 for (int j = 0; j < 16; ++j) if (j < qb && !((sel >> j) & 1u) && gate[j] > best) { best = gate[j]; bi = j; }
;                 if (bi >= 0) sel |= 1u << bi; }
;         }
;         { unsigned wsel = sel;
; #pragma unroll
;           for (int o = 1; o < 64; o <<= 1) wsel |= (unsigned)__shfl_xor((int)wsel, o);
;           if (lane == 0) ((LAS unsigned*)(lds + OFF_UM))[wave] = wsel; }
	v_cmp_gt_f32_e64 s[0:1], v10, v15
	s_and_b64 s[0:1], s[40:41], s[0:1]
	v_and_b32_e32 v16, 0x400, v13
	v_cndmask_b32_e64 v14, v14, 9, s[0:1]
	v_cndmask_b32_e64 v15, v15, v10, s[0:1]
	v_cmp_eq_u32_e64 s[0:1], 0, v16
	s_and_b64 s[40:41], s[54:55], s[0:1]
	v_cmp_gt_f32_e64 s[0:1], v11, v15
	s_and_b64 s[0:1], s[40:41], s[0:1]
	v_and_b32_e32 v16, 0x800, v13
	v_cndmask_b32_e64 v14, v14, 10, s[0:1]
	v_cndmask_b32_e64 v15, v15, v11, s[0:1]
	v_cmp_eq_u32_e64 s[0:1], 0, v16
	s_and_b64 s[40:41], s[52:53], s[0:1]
	v_cmp_gt_f32_e64 s[0:1], v12, v15
	s_and_b64 s[0:1], s[40:41], s[0:1]
	v_and_b32_e32 v16, 0x1000, v13
	v_cndmask_b32_e64 v14, v14, 11, s[0:1]
	v_cndmask_b32_e64 v15, v15, v12, s[0:1]
	v_cmp_eq_u32_e64 s[0:1], 0, v16
	s_and_b64 s[40:41], s[16:17], s[0:1]
	v_cmp_gt_f32_e64 s[0:1], v6, v15
	s_and_b64 s[0:1], s[40:41], s[0:1]
	v_and_b32_e32 v16, 0x2000, v13
	v_cndmask_b32_e64 v14, v14, 12, s[0:1]
	v_cndmask_b32_e64 v15, v15, v6, s[0:1]
	v_cmp_eq_u32_e64 s[0:1], 0, v16
	s_and_b64 s[40:41], s[14:15], s[0:1]
	v_cmp_gt_f32_e64 s[0:1], v7, v15
	s_and_b64 s[0:1], s[40:41], s[0:1]
	v_and_b32_e32 v16, 0x4000, v13
	v_cndmask_b32_e64 v14, v14, 13, s[0:1]
	v_cndmask_b32_e64 v15, v15, v7, s[0:1]
	v_cmp_eq_u32_e64 s[0:1], 0, v16
	s_and_b64 s[40:41], s[12:13], s[0:1]
	v_cmp_gt_f32_e64 s[0:1], v8, v15
	s_and_b64 s[0:1], s[40:41], s[0:1]
	v_and_b32_e32 v16, 0x8000, v13
	v_cndmask_b32_e64 v14, v14, 14, s[0:1]
	v_cndmask_b32_e64 v15, v15, v8, s[0:1]
	v_cmp_eq_u32_e64 s[0:1], 0, v16
	s_and_b64 s[40:41], s[4:5], s[0:1]
	v_cmp_gt_f32_e64 s[0:1], v9, v15
	s_and_b64 s[0:1], s[40:41], s[0:1]
	s_nop 0
	v_cndmask_b32_e64 v14, v14, 15, s[0:1]
	v_lshlrev_b32_e64 v15, v14, 1
	v_cmp_lt_i32_e64 s[0:1], -1, v14
	s_nop 1
	v_cndmask_b32_e64 v14, 0, v15, s[0:1]
	v_or_b32_e32 v15, v14, v13
	v_and_b32_e32 v16, 1, v15
	v_cmp_eq_u32_e64 s[0:1], 1, v16
	s_or_b64 vcc, vcc, s[0:1]
	v_bitop3_b32 v21, v14, 2, v13 bitop3:0xc8
	v_cndmask_b32_e64 v16, 0, -1, vcc
	v_cndmask_b32_e32 v17, v17, v217, vcc
	v_cmp_eq_u32_e32 vcc, 0, v21
	s_and_b64 s[0:1], s[74:75], vcc
	v_cmp_gt_f32_e32 vcc, v18, v17
	s_and_b64 vcc, s[0:1], vcc
	s_nop 0
	v_cndmask_b32_e32 v17, v17, v18, vcc
	v_bitop3_b32 v18, v14, 4, v13 bitop3:0xc8
	v_cndmask_b32_e64 v16, v16, 1, vcc
	v_cmp_eq_u32_e32 vcc, 0, v18
	s_and_b64 s[0:1], s[72:73], vcc
	v_cmp_gt_f32_e32 vcc, v19, v17
	s_and_b64 vcc, s[0:1], vcc
	v_bitop3_b32 v18, v14, 8, v13 bitop3:0xc8
	v_cndmask_b32_e64 v16, v16, 2, vcc
	v_cndmask_b32_e32 v17, v17, v19, vcc
	v_cmp_eq_u32_e32 vcc, 0, v18
	s_and_b64 s[0:1], s[70:71], vcc
	v_cmp_gt_f32_e32 vcc, v20, v17
	s_and_b64 vcc, s[0:1], vcc
	v_bitop3_b32 v18, v14, 16, v13 bitop3:0xc8
	v_cndmask_b32_e64 v16, v16, 3, vcc
	v_cndmask_b32_e32 v17, v17, v20, vcc
	v_cmp_eq_u32_e32 vcc, 0, v18
	s_and_b64 s[0:1], s[66:67], vcc
	v_cmp_gt_f32_e32 vcc, v1, v17
	s_and_b64 vcc, s[0:1], vcc
	s_nop 0
	v_cndmask_b32_e32 v1, v17, v1, vcc
	v_bitop3_b32 v17, v14, 32, v13 bitop3:0xc8
	v_cndmask_b32_e64 v16, v16, 4, vcc
	v_cmp_eq_u32_e32 vcc, 0, v17
	s_and_b64 s[0:1], s[64:65], vcc
	v_cmp_gt_f32_e32 vcc, v2, v1
	s_and_b64 vcc, s[0:1], vcc
	s_nop 0
	v_cndmask_b32_e32 v1, v1, v2, vcc
	v_bitop3_b32 v2, v14, 64, v13 bitop3:0xc8
	v_cndmask_b32_e64 v16, v16, 5, vcc
	v_cmp_eq_u32_e32 vcc, 0, v2
	s_and_b64 s[0:1], s[62:63], vcc
	v_cmp_gt_f32_e32 vcc, v3, v1
	s_and_b64 vcc, s[0:1], vcc
	s_movk_i32 s0, 0x80
	v_cndmask_b32_e32 v1, v1, v3, vcc
	v_bitop3_b32 v3, v14, s0, v13 bitop3:0xc8
	v_cndmask_b32_e64 v2, v16, 6, vcc
	v_cmp_eq_u32_e32 vcc, 0, v3
	s_and_b64 s[0:1], s[60:61], vcc
	v_cmp_gt_f32_e32 vcc, v4, v1
	s_and_b64 vcc, s[0:1], vcc
	s_movk_i32 s0, 0x100
	v_bitop3_b32 v3, v14, s0, v13 bitop3:0xc8
	v_cndmask_b32_e64 v2, v2, 7, vcc
	v_cndmask_b32_e32 v1, v1, v4, vcc
	v_cmp_eq_u32_e32 vcc, 0, v3
	s_and_b64 s[0:1], s[58:59], vcc
	v_cmp_gt_f32_e32 vcc, v5, v1
	s_and_b64 vcc, s[0:1], vcc
	s_movk_i32 s0, 0x200
	v_bitop3_b32 v3, v14, s0, v13 bitop3:0xc8
	v_cndmask_b32_e64 v2, v2, 8, vcc
	v_cndmask_b32_e32 v1, v1, v5, vcc
	v_cmp_eq_u32_e32 vcc, 0, v3
	s_and_b64 s[0:1], s[56:57], vcc
	v_cmp_gt_f32_e32 vcc, v10, v1
	s_and_b64 vcc, s[0:1], vcc
	s_movk_i32 s0, 0x400
	v_bitop3_b32 v3, v14, s0, v13 bitop3:0xc8
	v_cndmask_b32_e64 v2, v2, 9, vcc
	v_cndmask_b32_e32 v1, v1, v10, vcc
	v_cmp_eq_u32_e32 vcc, 0, v3
	s_and_b64 s[0:1], s[54:55], vcc
	v_cmp_gt_f32_e32 vcc, v11, v1
	s_and_b64 vcc, s[0:1], vcc
	s_movk_i32 s0, 0x800
	v_bitop3_b32 v3, v14, s0, v13 bitop3:0xc8
	v_cndmask_b32_e64 v2, v2, 10, vcc
	v_cndmask_b32_e32 v1, v1, v11, vcc
	v_cmp_eq_u32_e32 vcc, 0, v3
	s_and_b64 s[0:1], s[52:53], vcc
	v_cmp_gt_f32_e32 vcc, v12, v1
	s_and_b64 vcc, s[0:1], vcc
	s_movk_i32 s0, 0x1000
	v_bitop3_b32 v3, v14, s0, v13 bitop3:0xc8
	v_cndmask_b32_e64 v2, v2, 11, vcc
	v_cndmask_b32_e32 v1, v1, v12, vcc
	v_cmp_eq_u32_e32 vcc, 0, v3
	s_and_b64 s[0:1], s[16:17], vcc
	v_cmp_gt_f32_e32 vcc, v6, v1
	s_and_b64 vcc, s[0:1], vcc
	s_movk_i32 s0, 0x2000
	v_bitop3_b32 v3, v14, s0, v13 bitop3:0xc8
	v_cndmask_b32_e64 v2, v2, 12, vcc
	v_cndmask_b32_e32 v1, v1, v6, vcc
	v_cmp_eq_u32_e32 vcc, 0, v3
	s_and_b64 s[0:1], s[14:15], vcc
	v_cmp_gt_f32_e32 vcc, v7, v1
	s_and_b64 vcc, s[0:1], vcc
	s_movk_i32 s0, 0x4000
	v_bitop3_b32 v3, v14, s0, v13 bitop3:0xc8
	v_cndmask_b32_e64 v2, v2, 13, vcc
	v_cndmask_b32_e32 v1, v1, v7, vcc
	v_cmp_eq_u32_e32 vcc, 0, v3
	s_and_b64 s[0:1], s[12:13], vcc
	v_cmp_gt_f32_e32 vcc, v8, v1
	s_and_b64 vcc, s[0:1], vcc
	s_mov_b32 s0, 0x8000
	v_bitop3_b32 v3, v14, s0, v13 bitop3:0xc8
	v_cndmask_b32_e64 v2, v2, 14, vcc
	v_cndmask_b32_e32 v1, v1, v8, vcc
	v_cmp_eq_u32_e32 vcc, 0, v3
	s_and_b64 s[0:1], s[4:5], vcc
	v_cmp_gt_f32_e32 vcc, v9, v1
	s_and_b64 s[0:1], s[0:1], vcc
	v_cndmask_b32_e64 v1, v2, 15, s[0:1]
	v_lshlrev_b32_e64 v2, v1, 1
	v_cmp_lt_i32_e32 vcc, -1, v1
	v_mov_b32_e32 v3, v0
	v_mov_b32_e32 v6, v0
	v_cndmask_b32_e32 v1, 0, v2, vcc
	v_or_b32_e32 v201, v1, v15
	ds_bpermute_b32 v1, v210, v201
	v_mov_b32_e32 v7, v0
	v_mov_b32_e32 v10, v0
	v_mov_b32_e32 v11, v0
	v_mov_b32_e32 v14, v0
	s_waitcnt lgkmcnt(0)
	v_or_b32_e32 v1, v201, v1
	ds_bpermute_b32 v2, v211, v1
	v_mov_b32_e32 v15, v0
	s_waitcnt lgkmcnt(0)
	v_or_b32_e32 v4, v1, v2
	ds_bpermute_b32 v5, v212, v4
	v_mov_b32_e32 v1, v0
	v_mov_b32_e32 v2, v0
	s_waitcnt lgkmcnt(0)
	v_or_b32_e32 v8, v4, v5
	ds_bpermute_b32 v9, v213, v8
	v_mov_b32_e32 v4, v0
	v_mov_b32_e32 v5, v0
	s_waitcnt lgkmcnt(0)
	v_or_b32_e32 v12, v8, v9
	ds_bpermute_b32 v13, v214, v12
	v_mov_b32_e32 v8, v0
	v_mov_b32_e32 v9, v0
	s_waitcnt lgkmcnt(0)
	v_or_b32_e32 v16, v12, v13
	ds_bpermute_b32 v17, v193, v16
	v_mov_b32_e32 v12, v0
	v_mov_b32_e32 v13, v0
	s_mov_b64 s[0:1], exec
	v_readlane_b32 s4, v255, 6
	v_readlane_b32 s5, v255, 7
	s_and_b64 s[4:5], s[0:1], s[4:5]
	s_mov_b64 exec, s[4:5]
	s_cbranch_execz .LBB0_737
	v_readlane_b32 s4, v255, 8
	s_waitcnt lgkmcnt(0)
	v_or_b32_e32 v16, v16, v17
	v_mov_b32_e32 v17, s4
	ds_write_b32 v17, v16
; #define LAS __attribute__((address_space(3)))
; #define MOBA_LOAD(jj, kk) do { const size_t r_ = (rowb + (jj) * 256 + (kk) * 64 + lrow) * D_ + h * 128 + lc * 16; rk0 = *(const u32x4*)(MBK + r_); rk1 = *(const u32x4*)(MBK + r_ + 8); rv0 = *(const u32x4*)(MBV + r_); rv1 = *(const u32x4*)(MBV + r_ + 8); } while (0)
; #define MOBA_STORE(bb) do { LAS unsigned char* kd = lds + OFF_K + (bb) * 64 * KST + lrow * KST + lc * 32; *(LAS u32x4*)kd = rk0; *(LAS u32x4*)(kd + 16) = rk1; \
;         LAS unsigned char* vd = lds + OFF_V + (bb) * 64 * VST + lrow * VST + lc * 32; *(LAS u32x4*)vd = rv0; *(LAS u32x4*)(vd + 16) = rv1; } while (0)
; __device__ __forceinline__ void phase_moba_mfma(const Params& p, LAS unsigned char* lds, unsigned lds_base) {
;     ...
;         __syncthreads();
;         unsigned um = 0;
; #pragma unroll
;         for (int w = 0; w < 8; ++w) um |= ((const LAS unsigned*)(lds + OFF_UM))[w];
;         um = __builtin_amdgcn_readfirstlane(um);
;         f32x16 O[4];
; #pragma unroll
;         for (int dt = 0; dt < 4; ++dt)
; #pragma unroll
;             for (int r = 0; r < 16; ++r) O[dt][r] = 0.f;
;         float m = NINF, l = 0.f;
;         int j = qb, kt = 0, buf = 0;
;         u32x4 rk0, rk1, rv0, rv1;
;     ...
;         MOBA_LOAD(j, kt); MOBA_STORE(0); __syncthreads();
.LBB0_737:
	s_or_b64 exec, exec, s[0:1]
	s_add_i32 s0, 16, 0x15a00
	v_mov_b32_e32 v16, s0
	s_waitcnt lgkmcnt(0)
	s_barrier
	ds_read_b128 v[16:19], v16
	s_lshl_b32 s4, s11, 7
	s_add_u32 s0, s7, s10
	s_addc_u32 s1, 0, 0
	v_or_b32_e32 v206, s4, v190
	s_waitcnt lgkmcnt(0)
	v_or_b32_e32 v16, v17, v16
	v_or_b32_e32 v16, v16, v18
	v_or_b32_e32 v20, v16, v19
	v_mov_b32_e32 v16, s20
	ds_read_b128 v[16:19], v16
	v_mov_b64_e32 v[64:65], v[14:15]
	v_mov_b64_e32 v[48:49], v[14:15]
	v_mov_b64_e32 v[62:63], v[12:13]
	v_mov_b64_e32 v[60:61], v[10:11]
	s_waitcnt lgkmcnt(0)
	v_or_b32_e32 v16, v20, v16
	v_or_b32_e32 v16, v16, v17
	v_or_b32_e32 v16, v16, v18
	v_or_b32_e32 v16, v16, v19
	v_mov_b64_e32 v[58:59], v[8:9]
	v_readfirstlane_b32 s68, v16
	v_mov_b64_e32 v[32:33], v[14:15]
	v_mov_b64_e32 v[56:57], v[6:7]
	v_mov_b64_e32 v[54:55], v[4:5]
	v_mov_b64_e32 v[52:53], v[2:3]
	v_mov_b64_e32 v[50:51], v[0:1]
	v_mov_b64_e32 v[46:47], v[12:13]
	v_mov_b64_e32 v[44:45], v[10:11]
	v_mov_b64_e32 v[42:43], v[8:9]
	v_mov_b64_e32 v[40:41], v[6:7]
	v_mov_b64_e32 v[38:39], v[4:5]
	v_mov_b64_e32 v[36:37], v[2:3]
	v_mov_b64_e32 v[34:35], v[0:1]
	v_mov_b64_e32 v[30:31], v[12:13]
	v_mov_b64_e32 v[28:29], v[10:11]
	v_mov_b64_e32 v[26:27], v[8:9]
	v_mov_b64_e32 v[24:25], v[6:7]
	v_mov_b64_e32 v[22:23], v[4:5]
	v_mov_b64_e32 v[20:21], v[2:3]
	v_mov_b64_e32 v[18:19], v[0:1]
	v_mov_b64_e32 v[16:17], v[14:15]
	s_and_b32 s7, s2, 48
	v_or_b32_e32 v218, s6, v178
	s_mov_b32 s37, 0
	s_waitcnt vmcnt(8)
	v_mov_b32_e32 v208, v204
	v_mov_b32_e32 v209, v204
	v_mov_b32_e32 v220, 0xff800000
	v_mov_b32_e32 v219, 0
	v_mov_b64_e32 v[14:15], v[12:13]
	v_mov_b64_e32 v[12:13], v[10:11]
	v_mov_b64_e32 v[10:11], v[8:9]
	v_mov_b64_e32 v[8:9], v[6:7]
	v_mov_b64_e32 v[6:7], v[4:5]
	v_mov_b64_e32 v[4:5], v[2:3]
	v_mov_b64_e32 v[2:3], v[0:1]
	s_mov_b32 s19, s36
	s_mov_b32 s2, 0
	s_mov_b32 s10, s36
	s_waitcnt vmcnt(4)
	s_waitcnt lgkmcnt(0)
	s_barrier
	s_mov_b32 s11, 1
	s_mov_b32 s101, 0
	s_mov_b32 s100, 0
	s_branch .Lmoba_top

;     __device__ __forceinline__ void operator()(const Acc& acc, const Unit& u, int wr, int wc, int fr, int fq) const {
;         const int row0 = u.pm * BM + wr * 64 + fr, col0 = u.pn * BM + wc * 32 + 4 * fq;
;         const float* g = gada + (size_t)(u.pm >> 4) * NADA;
;         f32x4 gv[2][2];
; #pragma unroll
;         for (int bj = 0; bj < 2; ++bj)
; #pragma unroll
;             for (int n = 0; n < 2; ++n) gv[bj][n] = *(const f32x4*)(g + col0 + bj * HALF + n * 16) * scale;
; #pragma unroll
;         for (int ai = 0; ai < 2; ++ai) {
;             f32x4 rr[4][2][2];
; #pragma unroll
;             for (int m = 0; m < 4; ++m)
; #pragma unroll
;                 for (int bj = 0; bj < 2; ++bj)
; #pragma unroll
;                     for (int n = 0; n < 2; ++n) rr[m][bj][n] = *(const f32x4*)(resid + (size_t)(row0 + ai * HALF + m * 16) * D_ + col0 + bj * HALF + n * 16);
; #pragma unroll
;             for (int m = 0; m < 4; ++m)
; #pragma unroll
;                 for (int bj = 0; bj < 2; ++bj)
; #pragma unroll
;                     for (int n = 0; n < 2; ++n) *(f32x4*)(out + (size_t)(row0 + ai * HALF + m * 16) * D_ + col0 + bj * HALF + n * 16) = rr[m][bj][n] + gv[bj][n] * acc[ai][bj][m][n];
.LBB0_1228:
	s_ashr_i32 s22, s48, 4
	v_lshl_or_b32 v140, s49, 8, v164
	s_mul_hi_i32 s23, s22, 0x12000
	s_mul_i32 s22, s22, 0x12000
	s_add_u32 s22, s39, s22
	v_ashrrev_i32_e32 v141, 31, v140
	s_addc_u32 s23, s40, s23
	v_lshlrev_b64 v[152:153], 2, v[140:141]
	v_lshl_add_u64 v[158:159], s[22:23], 0, v[152:153]
	global_load_dwordx4 v[140:143], v[158:159], off
	global_load_dwordx4 v[168:171], v[158:159], off offset:64
	global_load_dwordx4 v[172:175], v[158:159], off offset:512
	global_load_dwordx4 v[176:179], v[158:159], off offset:576
	v_lshl_add_u32 v216, s48, 8, v162
	v_ashrrev_i32_e32 v217, 31, v216
	v_or_b32_e32 v184, 16, v216
	v_ashrrev_i32_e32 v185, 31, v184
	v_lshlrev_b64 v[232:233], 13, v[184:185]
	v_or_b32_e32 v200, 32, v216
	v_ashrrev_i32_e32 v201, 31, v200
	v_lshlrev_b64 v[234:235], 13, v[200:201]
	s_mov_b64 s[22:23], -1
	s_and_b64 vcc, exec, s[0:1]
	s_waitcnt vmcnt(0)
	v_pk_mul_f32 v[154:155], v[142:143], 0.5 op_sel_hi:[1,0]
	v_pk_mul_f32 v[156:157], v[140:141], 0.5 op_sel_hi:[1,0]
	v_pk_mul_f32 v[148:149], v[170:171], 0.5 op_sel_hi:[1,0]
	v_pk_mul_f32 v[150:151], v[168:169], 0.5 op_sel_hi:[1,0]
	v_pk_mul_f32 v[144:145], v[174:175], 0.5 op_sel_hi:[1,0]
	v_pk_mul_f32 v[146:147], v[172:173], 0.5 op_sel_hi:[1,0]
	v_pk_mul_f32 v[140:141], v[178:179], 0.5 op_sel_hi:[1,0]
	v_pk_mul_f32 v[142:143], v[176:177], 0.5 op_sel_hi:[1,0]
	v_lshl_add_u64 v[158:159], s[24:25], 0, v[152:153]
	v_lshlrev_b64 v[160:161], 13, v[216:217]
	v_lshl_add_u64 v[180:181], v[158:159], 0, v[160:161]
	global_load_dwordx4 v[168:171], v[180:181], off
	global_load_dwordx4 v[172:175], v[180:181], off offset:64
	global_load_dwordx4 v[176:179], v[180:181], off offset:512
	s_nop 0
	global_load_dwordx4 v[180:183], v[180:181], off offset:576
	v_lshl_add_u64 v[196:197], v[158:159], 0, v[232:233]
	global_load_dwordx4 v[184:187], v[196:197], off
	global_load_dwordx4 v[188:191], v[196:197], off offset:64
	global_load_dwordx4 v[192:195], v[196:197], off offset:512
	s_nop 0
	global_load_dwordx4 v[196:199], v[196:197], off offset:576
	v_or_b32_e32 v216, 48, v216
	v_lshl_add_u64 v[212:213], v[158:159], 0, v[234:235]
	v_ashrrev_i32_e32 v217, 31, v216
	global_load_dwordx4 v[200:203], v[212:213], off
	global_load_dwordx4 v[204:207], v[212:213], off offset:64
	global_load_dwordx4 v[208:211], v[212:213], off offset:512
	s_nop 0
	global_load_dwordx4 v[212:215], v[212:213], off offset:576
	v_lshlrev_b64 v[236:237], 13, v[216:217]
	v_lshl_add_u64 v[228:229], v[158:159], 0, v[236:237]
	global_load_dwordx4 v[216:219], v[228:229], off
	global_load_dwordx4 v[220:223], v[228:229], off offset:64
	global_load_dwordx4 v[224:227], v[228:229], off offset:512
	s_nop 0
	global_load_dwordx4 v[228:231], v[228:229], off offset:576
	s_waitcnt vmcnt(15)
	v_pk_fma_f32 v[124:125], v[124:125], v[156:157], v[168:169]
	v_lshl_add_u64 v[168:169], s[24:25], 0, v[160:161]
	v_lshl_add_u64 v[168:169], v[168:169], 0, v[152:153]
	s_waitcnt vmcnt(13)
	v_pk_fma_f32 v[110:111], v[110:111], v[144:145], v[178:179]
	v_pk_fma_f32 v[108:109], v[108:109], v[146:147], v[176:177]
	global_store_dwordx4 v[168:169], v[108:111], off offset:512
	s_waitcnt vmcnt(10)
	v_pk_fma_f32 v[94:95], v[94:95], v[144:145], v[194:195]
	v_pk_fma_f32 v[92:93], v[92:93], v[146:147], v[192:193]
	v_lshl_add_u64 v[108:109], s[24:25], 0, v[232:233]
	v_lshl_add_u64 v[108:109], v[108:109], 0, v[152:153]
	global_store_dwordx4 v[108:109], v[92:95], off offset:512
	v_pk_fma_f32 v[102:103], v[102:103], v[140:141], v[182:183]
	v_pk_fma_f32 v[100:101], v[100:101], v[142:143], v[180:181]
	v_lshl_add_u64 v[92:93], s[24:25], 0, v[234:235]
	v_lshl_add_u64 v[92:93], v[92:93], 0, v[152:153]
	s_waitcnt vmcnt(7)
	v_pk_fma_f32 v[78:79], v[78:79], v[144:145], v[210:211]
	v_pk_fma_f32 v[76:77], v[76:77], v[146:147], v[208:209]
	global_store_dwordx4 v[168:169], v[100:103], off offset:576
	v_pk_fma_f32 v[86:87], v[86:87], v[140:141], v[198:199]
	v_pk_fma_f32 v[84:85], v[84:85], v[142:143], v[196:197]
	v_pk_fma_f32 v[102:103], v[118:119], v[154:155], v[186:187]
	v_pk_fma_f32 v[100:101], v[116:117], v[156:157], v[184:185]
	global_store_dwordx4 v[92:93], v[76:79], off offset:512
	s_waitcnt vmcnt(8)
	v_pk_fma_f32 v[74:75], v[74:75], v[140:141], v[214:215]
	v_pk_fma_f32 v[72:73], v[72:73], v[142:143], v[212:213]
	v_lshl_add_u64 v[76:77], s[24:25], 0, v[236:237]
	global_store_dwordx4 v[108:109], v[100:103], off
	global_store_dwordx4 v[108:109], v[84:87], off offset:576
	global_store_dwordx4 v[92:93], v[72:75], off offset:576
	v_pk_fma_f32 v[102:103], v[114:115], v[148:149], v[190:191]
	v_pk_fma_f32 v[100:101], v[112:113], v[150:151], v[188:189]
	v_pk_fma_f32 v[86:87], v[106:107], v[154:155], v[202:203]
	v_pk_fma_f32 v[84:85], v[104:105], v[156:157], v[200:201]
	s_waitcnt vmcnt(10)
	v_pk_fma_f32 v[74:75], v[90:91], v[154:155], v[218:219]
	v_pk_fma_f32 v[72:73], v[88:89], v[156:157], v[216:217]
	v_lshl_add_u64 v[76:77], v[76:77], 0, v[152:153]
	v_pk_fma_f32 v[126:127], v[126:127], v[154:155], v[170:171]
	v_pk_fma_f32 v[122:123], v[122:123], v[148:149], v[174:175]
	v_pk_fma_f32 v[120:121], v[120:121], v[150:151], v[172:173]
	global_store_dwordx4 v[108:109], v[100:103], off offset:64
	global_store_dwordx4 v[92:93], v[84:87], off
	global_store_dwordx4 v[76:77], v[72:75], off
	s_waitcnt vmcnt(11)
; #define PG8_BAR __builtin_amdgcn_s_barrier()
;     __device__ __forceinline__ void operator()(const Acc& acc, const Unit& u, int wr, int wc, int fr, int fq) const {
;     ...
;         for (int ai = 0; ai < 2; ++ai) {
;             f32x4 rr[4][2][2];
; #pragma unroll
;             for (int m = 0; m < 4; ++m)
; #pragma unroll
;                 for (int bj = 0; bj < 2; ++bj)
; #pragma unroll
;                     for (int n = 0; n < 2; ++n) rr[m][bj][n] = *(const f32x4*)(resid + (size_t)(row0 + ai * HALF + m * 16) * D_ + col0 + bj * HALF + n * 16);
; #pragma unroll
;             for (int m = 0; m < 4; ++m)
; #pragma unroll
;                 for (int bj = 0; bj < 2; ++bj)
; #pragma unroll
;                     for (int n = 0; n < 2; ++n) *(f32x4*)(out + (size_t)(row0 + ai * HALF + m * 16) * D_ + col0 + bj * HALF + n * 16) = rr[m][bj][n] + gv[bj][n] * acc[ai][bj][m][n];
; template <class Epi>
; __device__ __forceinline__ void gemm_phase(LAS unsigned char* lds, const Gemm g, const StaticOrder& S, const Epi& E) {
;     ...
;         if (!has_next) break;
; #pragma unroll
;         for (int a = 0; a < 2; ++a)
; #pragma unroll
;             for (int b = 0; b < 2; ++b)
; #pragma unroll
;                 for (int m = 0; m < 4; ++m)
; #pragma unroll
;                     for (int n = 0; n < 2; ++n) acc[a][b][m][n] = (f32x4){0.f, 0.f, 0.f, 0.f};
;         cur = nxt; cA = nA; cB = nB; ++ui;
;         if (wr == 1) PG8_BAR;
	v_pk_fma_f32 v[70:71], v[70:71], v[144:145], v[226:227]
	v_pk_fma_f32 v[86:87], v[98:99], v[148:149], v[206:207]
	v_pk_fma_f32 v[84:85], v[96:97], v[150:151], v[204:205]
	v_pk_fma_f32 v[74:75], v[82:83], v[148:149], v[222:223]
	v_pk_fma_f32 v[72:73], v[80:81], v[150:151], v[220:221]
	v_pk_fma_f32 v[68:69], v[68:69], v[146:147], v[224:225]
	s_waitcnt vmcnt(10)
	v_pk_fma_f32 v[66:67], v[66:67], v[140:141], v[230:231]
	v_pk_fma_f32 v[64:65], v[64:65], v[142:143], v[228:229]
	v_lshl_add_u64 v[108:109], v[160:161], 0, s[14:15]
	global_store_dwordx4 v[168:169], v[124:127], off
	global_store_dwordx4 v[168:169], v[120:123], off offset:64
	global_store_dwordx4 v[92:93], v[84:87], off offset:64
	global_store_dwordx4 v[76:77], v[72:75], off offset:64
	global_store_dwordx4 v[76:77], v[68:71], off offset:512
	global_store_dwordx4 v[76:77], v[64:67], off offset:576
	v_lshl_add_u64 v[106:107], v[160:161], 0, s[16:17]
	v_lshl_add_u64 v[104:105], v[160:161], 0, s[18:19]
	v_lshl_add_u64 v[64:65], v[158:159], 0, v[108:109]
	global_load_dwordx4 v[92:95], v[64:65], off
	global_load_dwordx4 v[88:91], v[64:65], off offset:64
	global_load_dwordx4 v[80:83], v[64:65], off offset:512
	global_load_dwordx4 v[76:79], v[64:65], off offset:576
	v_lshl_add_u64 v[64:65], v[158:159], 0, v[106:107]
	global_load_dwordx4 v[84:87], v[64:65], off
	global_load_dwordx4 v[72:75], v[64:65], off offset:64
	global_load_dwordx4 v[68:71], v[64:65], off offset:512
	s_nop 0
	global_load_dwordx4 v[64:67], v[64:65], off offset:576
	v_lshl_add_u64 v[96:97], v[158:159], 0, v[104:105]
	global_load_dwordx4 v[110:113], v[96:97], off
	global_load_dwordx4 v[114:117], v[96:97], off offset:64
	global_load_dwordx4 v[118:121], v[96:97], off offset:512
	global_load_dwordx4 v[122:125], v[96:97], off offset:576
	v_lshl_add_u64 v[126:127], v[160:161], 0, s[6:7]
	v_lshl_add_u64 v[96:97], v[158:159], 0, v[126:127]
	global_load_dwordx4 v[158:161], v[96:97], off
	global_load_dwordx4 v[168:171], v[96:97], off offset:64
	global_load_dwordx4 v[100:103], v[96:97], off offset:512
	s_nop 0
	global_load_dwordx4 v[96:99], v[96:97], off offset:576
	s_waitcnt vmcnt(15)
	v_pk_fma_f32 v[60:61], v[60:61], v[156:157], v[92:93]
	v_lshl_add_u64 v[92:93], s[24:25], 0, v[108:109]
	v_lshl_add_u64 v[92:93], v[92:93], 0, v[152:153]
	s_waitcnt vmcnt(13)
	v_pk_fma_f32 v[50:51], v[50:51], v[144:145], v[82:83]
	v_pk_fma_f32 v[48:49], v[48:49], v[146:147], v[80:81]
	global_store_dwordx4 v[92:93], v[48:51], off offset:512
	s_waitcnt vmcnt(10)
	v_pk_fma_f32 v[34:35], v[34:35], v[144:145], v[70:71]
	v_pk_fma_f32 v[32:33], v[32:33], v[146:147], v[68:69]
	v_lshl_add_u64 v[48:49], s[24:25], 0, v[106:107]
	v_lshl_add_u64 v[48:49], v[48:49], 0, v[152:153]
	global_store_dwordx4 v[48:49], v[32:35], off offset:512
	s_waitcnt vmcnt(7)
	v_pk_fma_f32 v[18:19], v[18:19], v[144:145], v[120:121]
	v_pk_fma_f32 v[16:17], v[16:17], v[146:147], v[118:119]
	v_lshl_add_u64 v[32:33], s[24:25], 0, v[104:105]
	v_lshl_add_u64 v[32:33], v[32:33], 0, v[152:153]
	v_pk_fma_f32 v[42:43], v[42:43], v[140:141], v[78:79]
	v_pk_fma_f32 v[40:41], v[40:41], v[142:143], v[76:77]
	v_pk_fma_f32 v[26:27], v[26:27], v[140:141], v[66:67]
	v_pk_fma_f32 v[24:25], v[24:25], v[142:143], v[64:65]
	global_store_dwordx4 v[32:33], v[16:19], off offset:512
	s_waitcnt vmcnt(7)
	v_pk_fma_f32 v[10:11], v[10:11], v[140:141], v[124:125]
	v_pk_fma_f32 v[8:9], v[8:9], v[142:143], v[122:123]
	v_lshl_add_u64 v[16:17], s[24:25], 0, v[126:127]
	global_store_dwordx4 v[92:93], v[40:43], off offset:576
	global_store_dwordx4 v[48:49], v[24:27], off offset:576
	global_store_dwordx4 v[32:33], v[8:11], off offset:576
	v_pk_fma_f32 v[42:43], v[54:55], v[154:155], v[86:87]
	v_pk_fma_f32 v[40:41], v[52:53], v[156:157], v[84:85]
	v_pk_fma_f32 v[26:27], v[38:39], v[154:155], v[112:113]
	v_pk_fma_f32 v[24:25], v[36:37], v[156:157], v[110:111]
	s_waitcnt vmcnt(9)
	v_pk_fma_f32 v[10:11], v[22:23], v[154:155], v[160:161]
	v_pk_fma_f32 v[8:9], v[20:21], v[156:157], v[158:159]
	v_lshl_add_u64 v[16:17], v[16:17], 0, v[152:153]
	v_pk_fma_f32 v[62:63], v[62:63], v[154:155], v[94:95]
	v_pk_fma_f32 v[58:59], v[58:59], v[148:149], v[90:91]
	v_pk_fma_f32 v[56:57], v[56:57], v[150:151], v[88:89]
	global_store_dwordx4 v[48:49], v[40:43], off
	global_store_dwordx4 v[32:33], v[24:27], off
	global_store_dwordx4 v[16:17], v[8:11], off
	v_pk_fma_f32 v[42:43], v[46:47], v[148:149], v[74:75]
	v_pk_fma_f32 v[40:41], v[44:45], v[150:151], v[72:73]
	v_pk_fma_f32 v[26:27], v[30:31], v[148:149], v[116:117]
	v_pk_fma_f32 v[24:25], v[28:29], v[150:151], v[114:115]
	s_waitcnt vmcnt(11)
	v_pk_fma_f32 v[10:11], v[14:15], v[148:149], v[170:171]
	v_pk_fma_f32 v[8:9], v[12:13], v[150:151], v[168:169]
	s_waitcnt vmcnt(10)
	v_pk_fma_f32 v[6:7], v[6:7], v[144:145], v[102:103]
	v_pk_fma_f32 v[4:5], v[4:5], v[146:147], v[100:101]
	s_waitcnt vmcnt(9)
	v_pk_fma_f32 v[2:3], v[2:3], v[140:141], v[98:99]
	v_pk_fma_f32 v[0:1], v[0:1], v[142:143], v[96:97]
	global_store_dwordx4 v[92:93], v[60:63], off
	global_store_dwordx4 v[92:93], v[56:59], off offset:64
	global_store_dwordx4 v[48:49], v[40:43], off offset:64
	global_store_dwordx4 v[32:33], v[24:27], off offset:64
	global_store_dwordx4 v[16:17], v[8:11], off offset:64
	global_store_dwordx4 v[16:17], v[4:7], off offset:512
	global_store_dwordx4 v[16:17], v[0:3], off offset:576
	s_cbranch_vccnz .LBB0_1213
	s_andn2_b64 vcc, exec, s[8:9]
	s_cbranch_vccnz .LBB0_1212
	s_barrier
	s_branch .LBB0_1212
